# norm phase 9: scale/shift chunk-0 loads issued before the row-data wait (as the compiler already did in phases 12/16)
# speedup vs baseline: 1.0046x; 1.0025x over previous
; __device__ __forceinline__ u16 f2bf(float x) { unsigned u = __float_as_uint(x); u += 0x7fffu + ((u >> 16) & 1u); return (u16)(u >> 16); }
; __device__ __forceinline__ size_t a_off(int row, int col, int nks) { return ((size_t)((row >> 8) * nks + (col >> 5)) << 13) + ((row & 255) << 5) + swzc(row, col & 31); }
; template <int MODE>
; __device__ __forceinline__ void norm_phase(const Params& p, const float* src, const float* w, const float* modl, int sh_off, int sc_off,
;                            char* smem, int bid, int nblk) {
;     ...
;     for (int i = 0; i < 4; ++i) ss += v[i][0] * v[i][0] + v[i][1] * v[i][1] + v[i][2] * v[i][2] + v[i][3] * v[i][3];
; #pragma unroll
;     for (int o = 32; o >= 1; o >>= 1) ss += __shfl_xor(ss, o);
;     const float rstd = rsqrtf(ss * (1.f / 1024.f) + 1e-6f);
;     const int b = row >> 13;
;     float dots[8];
;     if (MODE == 1) { for (int j = 0; j < 8; ++j) dots[j] = 0.f; }
; #pragma unroll
;     for (int i = 0; i < 4; ++i) {
;       const int c0 = i * 256 + lane * 4;
;       f32x4 ww = *(const f32x4*)(w + c0);
;       f32x4 y;
;       if (MODE == 2) {
; #pragma unroll
;         for (int e = 0; e < 4; ++e) y[e] = v[i][e] * rstd * ww[e];
;         *(f32x4*)(p.out + (size_t)row * 1024 + c0) = y;
;       } else {
;         f32x4 sc = *(const f32x4*)(modl + (size_t)b * 6144 + sc_off + c0);
;         f32x4 sh = *(const f32x4*)(modl + (size_t)b * 6144 + sh_off + c0);
; #pragma unroll
;         for (int e = 0; e < 4; ++e) y[e] = v[i][e] * rstd * ww[e] * (1.f + sc[e]) + sh[e];
;         uint2 pk; pk.x = (unsigned)f2bf(y[0]) | ((unsigned)f2bf(y[1]) << 16); pk.y = (unsigned)f2bf(y[2]) | ((unsigned)f2bf(y[3]) << 16);
;         *(uint2*)(hn + a_off(row, c0, 32)) = pk;
.LBB0_1428:
	s_or_b64 exec, exec, s[0:1]
	v_ashrrev_i32_e32 v34, 13, v33
	v_mul_i32_i24_e32 v60, 0x1800, v34
	v_readlane_b32 s0, v244, 23
	v_ashrrev_i32_e32 v61, 31, v60
	v_readlane_b32 s1, v244, 24
	global_load_dwordx4 v[82:85], v[38:39], off
	v_lshl_add_u64 v[62:63], v[60:61], 2, s[0:1]
	v_lshl_add_u64 v[60:61], v[62:63], 0, s[12:13]
	v_lshl_add_u64 v[86:87], v[60:61], 0, v[44:45]
	v_lshl_add_u64 v[62:63], v[62:63], 0, s[14:15]
	global_load_dwordx4 v[86:89], v[86:87], off
	v_lshl_add_u64 v[90:91], v[62:63], 0, v[44:45]
	global_load_dwordx4 v[90:93], v[90:91], off
	s_waitcnt vmcnt(2)
	v_pk_mul_f32 v[96:97], v[28:29], v[28:29]
	v_pk_mul_f32 v[98:99], v[24:25], v[24:25]
	v_pk_mul_f32 v[64:65], v[30:31], v[30:31]
	v_pk_mul_f32 v[94:95], v[26:27], v[26:27]
	v_mov_b32_e32 v100, v96
	v_mov_b32_e32 v101, v98
	v_mov_b32_e32 v98, v97
	v_pk_add_f32 v[96:97], v[100:101], v[98:99]
	v_mov_b32_e32 v98, v64
	v_mov_b32_e32 v99, v94
	v_pk_add_f32 v[96:97], v[98:99], v[96:97]
	v_mov_b32_e32 v94, v65
	v_pk_add_f32 v[64:65], v[94:95], v[96:97]
	v_mov_b32_e32 v96, v17
	v_mov_b32_e32 v97, v21
	v_mov_b32_e32 v94, v16
	v_mov_b32_e32 v95, v20
	v_pk_mul_f32 v[96:97], v[96:97], v[96:97]
	v_add_f32_e32 v34, v64, v65
	v_pk_fma_f32 v[94:95], v[94:95], v[94:95], v[96:97]
	v_mov_b32_e32 v96, v18
	v_mov_b32_e32 v97, v22
	v_pk_fma_f32 v[94:95], v[96:97], v[96:97], v[94:95]
	v_mov_b32_e32 v96, v19
	v_mov_b32_e32 v97, v23
	v_pk_fma_f32 v[94:95], v[96:97], v[96:97], v[94:95]
	v_and_b32_e32 v55, 24, v77
	v_add_f32_e32 v34, v95, v34
	v_add_f32_e32 v34, v94, v34
	s_nop 1
	v_mov_b32_e32 v43, v34
	s_nop 1
	v_permlane32_swap_b32_e32 v34, v43
	v_mov_b32_e32 v95, v30
	v_mov_b32_e32 v30, v29
	v_and_b32_e32 v51, 0x1fe0, v78
	v_sub_u32_e32 v55, 0, v55
	s_waitcnt lgkmcnt(0)
	v_add_f32_e32 v34, v34, v43
	s_nop 1
	v_mov_b32_e32 v43, v34
	s_nop 1
	v_permlane16_swap_b32_e32 v34, v43
	v_mov_b32_e32 v94, v28
	v_ashrrev_i32_e32 v47, 3, v33
	v_and_b32_e32 v47, 0xffffffe0, v47
	v_or_b32_e32 v28, v47, v72
	s_waitcnt lgkmcnt(0)
	v_add_f32_e32 v34, v34, v43
	s_nop 1
	v_mov_b32_dpp v43, v34 row_ror:8 row_mask:0xf bank_mask:0xf
	v_mov_b32_e32 v65, v35
	s_waitcnt lgkmcnt(0)
	v_add_f32_e32 v34, v34, v43
	s_nop 1
	v_mov_b32_dpp v43, v34 row_ror:4 row_mask:0xf bank_mask:0xf
	s_waitcnt lgkmcnt(0)
	v_add_f32_e32 v29, v34, v43
	s_nop 1
	v_mov_b32_dpp v43, v29 quad_perm:[2,3,0,1] row_mask:0xf bank_mask:0xf
	v_lshlrev_b32_e32 v34, 1, v51
	v_xor_b32_e32 v51, v32, v55
	v_and_or_b32 v51, v51, 24, v73
	v_lshlrev_b32_e32 v64, 1, v51
	s_waitcnt lgkmcnt(0)
	v_add_f32_e32 v43, v29, v43
	s_nop 1
	v_mov_b32_dpp v55, v43 quad_perm:[1,0,3,2] row_mask:0xf bank_mask:0xf
	v_ashrrev_i32_e32 v29, 31, v28
	v_lshlrev_b64 v[28:29], 14, v[28:29]
	v_lshl_add_u64 v[28:29], s[62:63], 0, v[28:29]
	v_lshl_add_u64 v[28:29], v[28:29], 0, v[34:35]
	s_waitcnt lgkmcnt(0)
	v_add_f32_e32 v43, v43, v55
	v_fmamk_f32 v43, v43, 0x3a800000, v79
	v_mul_f32_e32 v51, 0x4b800000, v43
	v_cmp_gt_f32_e64 s[0:1], s18, v43
	v_lshl_add_u64 v[28:29], v[28:29], 0, v[64:65]
	v_mov_b32_e32 v98, v82
	v_cndmask_b32_e64 v43, v43, v51, s[0:1]
	v_rsq_f32_e32 v43, v43
	v_mov_b32_e32 v99, v84
	v_mov_b32_e32 v84, v83
	v_mul_f32_e32 v51, 0x45800000, v43
	v_cndmask_b32_e64 v96, v43, v51, s[0:1]
	v_pk_mul_f32 v[94:95], v[94:95], v[96:97] op_sel_hi:[1,0]
	v_pk_mul_f32 v[30:31], v[30:31], v[96:97] op_sel_hi:[1,0]
	v_pk_mul_f32 v[82:83], v[98:99], v[94:95]
	s_waitcnt vmcnt(1)
	v_mov_b32_e32 v95, v88
	v_mov_b32_e32 v88, v87
	v_mov_b32_e32 v94, v86
	s_waitcnt vmcnt(0)
	v_mov_b32_e32 v99, v92
	v_pk_mul_f32 v[30:31], v[84:85], v[30:31]
	v_pk_add_f32 v[84:85], v[88:89], 1.0 op_sel_hi:[1,0]
	v_mov_b32_e32 v92, v91
	v_mov_b32_e32 v98, v90
	v_pk_add_f32 v[94:95], v[94:95], 1.0 op_sel_hi:[1,0]
	v_pk_fma_f32 v[30:31], v[84:85], v[30:31], v[92:93]
	v_pk_fma_f32 v[82:83], v[94:95], v[82:83], v[98:99]
	v_and_b32_sdwa v55, v31, v80 dst_sel:DWORD dst_unused:UNUSED_PAD src0_sel:WORD_1 src1_sel:DWORD
	v_and_b32_sdwa v59, v30, v80 dst_sel:DWORD dst_unused:UNUSED_PAD src0_sel:WORD_1 src1_sel:DWORD
	v_and_b32_sdwa v43, v83, v80 dst_sel:DWORD dst_unused:UNUSED_PAD src0_sel:WORD_1 src1_sel:DWORD
	v_and_b32_sdwa v51, v82, v80 dst_sel:DWORD dst_unused:UNUSED_PAD src0_sel:WORD_1 src1_sel:DWORD
	v_add3_u32 v31, v31, v55, s19
	v_add3_u32 v30, v30, v59, s19
	v_add3_u32 v51, v82, v51, s19
	v_add3_u32 v43, v83, v43, s19
	v_and_b32_e32 v31, 0xffff0000, v31
	v_and_b32_e32 v30, 0xffff0000, v30
	v_or_b32_sdwa v31, v31, v43 dst_sel:DWORD dst_unused:UNUSED_PAD src0_sel:DWORD src1_sel:WORD_1
	v_or_b32_sdwa v30, v30, v51 dst_sel:DWORD dst_unused:UNUSED_PAD src0_sel:DWORD src1_sel:WORD_1
	v_mov_b32_e32 v250, v28
	v_mov_b32_e32 v251, v29
	v_mov_b32_e32 v252, v30
	v_mov_b32_e32 v253, v31
	v_lshl_add_u64 v[82:83], v[60:61], 0, v[48:49]
	global_load_dwordx4 v[28:31], v[38:39], off offset:1024
	v_lshl_add_u64 v[86:87], v[62:63], 0, v[48:49]
	global_load_dwordx4 v[82:85], v[82:83], off
	v_mov_b32_e32 v91, v26
	global_load_dwordx4 v[86:89], v[86:87], off
	global_store_dwordx2 v[250:251], v[252:253], off
	v_mov_b32_e32 v26, v25
	v_mov_b32_e32 v90, v24
	v_pk_mul_f32 v[26:27], v[26:27], v[96:97] op_sel_hi:[1,0]
	v_or_b32_e32 v24, v47, v74
	v_pk_mul_f32 v[90:91], v[90:91], v[96:97] op_sel_hi:[1,0]
	v_ashrrev_i32_e32 v25, 31, v24
	v_lshlrev_b64 v[24:25], 14, v[24:25]
	v_lshl_add_u64 v[24:25], s[62:63], 0, v[24:25]
	v_lshl_add_u64 v[24:25], v[24:25], 0, v[34:35]
	v_lshl_add_u64 v[24:25], v[24:25], 0, v[64:65]
	s_waitcnt vmcnt(3)
	v_mov_b32_e32 v93, v30
	v_mov_b32_e32 v30, v29
	s_waitcnt vmcnt(2)
	v_mov_b32_e32 v95, v84
	v_mov_b32_e32 v84, v83
	v_mov_b32_e32 v92, v28
	v_mov_b32_e32 v94, v82
	s_waitcnt vmcnt(1)
; __device__ __forceinline__ u16 f2bf(float x) { unsigned u = __float_as_uint(x); u += 0x7fffu + ((u >> 16) & 1u); return (u16)(u >> 16); }
; __device__ __forceinline__ size_t a_off(int row, int col, int nks) { return ((size_t)((row >> 8) * nks + (col >> 5)) << 13) + ((row & 255) << 5) + swzc(row, col & 31); }
; template <int MODE>
; __device__ __forceinline__ void norm_phase(const Params& p, const float* src, const float* w, const float* modl, int sh_off, int sc_off,
;                            char* smem, int bid, int nblk) {
;     ...
;     for (int i = 0; i < 4; ++i) {
;       const int c0 = i * 256 + lane * 4;
;       f32x4 ww = *(const f32x4*)(w + c0);
;       f32x4 y;
;       if (MODE == 2) {
; #pragma unroll
;         for (int e = 0; e < 4; ++e) y[e] = v[i][e] * rstd * ww[e];
;         *(f32x4*)(p.out + (size_t)row * 1024 + c0) = y;
;       } else {
;         f32x4 sc = *(const f32x4*)(modl + (size_t)b * 6144 + sc_off + c0);
;         f32x4 sh = *(const f32x4*)(modl + (size_t)b * 6144 + sh_off + c0);
; #pragma unroll
;         for (int e = 0; e < 4; ++e) y[e] = v[i][e] * rstd * ww[e] * (1.f + sc[e]) + sh[e];
;         uint2 pk; pk.x = (unsigned)f2bf(y[0]) | ((unsigned)f2bf(y[1]) << 16); pk.y = (unsigned)f2bf(y[2]) | ((unsigned)f2bf(y[3]) << 16);
;         *(uint2*)(hn + a_off(row, c0, 32)) = pk;
	v_mov_b32_e32 v99, v88
	v_mov_b32_e32 v88, v87
	v_pk_mul_f32 v[26:27], v[30:31], v[26:27]
	v_pk_add_f32 v[30:31], v[84:85], 1.0 op_sel_hi:[1,0]
	v_mov_b32_e32 v98, v86
	v_pk_mul_f32 v[28:29], v[92:93], v[90:91]
	v_pk_add_f32 v[82:83], v[94:95], 1.0 op_sel_hi:[1,0]
	v_pk_fma_f32 v[26:27], v[30:31], v[26:27], v[88:89]
	v_pk_fma_f32 v[28:29], v[82:83], v[28:29], v[98:99]
	v_and_b32_sdwa v43, v27, v80 dst_sel:DWORD dst_unused:UNUSED_PAD src0_sel:WORD_1 src1_sel:DWORD
	v_and_b32_sdwa v51, v26, v80 dst_sel:DWORD dst_unused:UNUSED_PAD src0_sel:WORD_1 src1_sel:DWORD
	v_and_b32_sdwa v30, v29, v80 dst_sel:DWORD dst_unused:UNUSED_PAD src0_sel:WORD_1 src1_sel:DWORD
	v_and_b32_sdwa v31, v28, v80 dst_sel:DWORD dst_unused:UNUSED_PAD src0_sel:WORD_1 src1_sel:DWORD
	v_add3_u32 v27, v27, v43, s19
	v_add3_u32 v26, v26, v51, s19
	v_add3_u32 v28, v28, v31, s19
	v_add3_u32 v29, v29, v30, s19
	v_and_b32_e32 v27, 0xffff0000, v27
	v_and_b32_e32 v26, 0xffff0000, v26
	v_or_b32_sdwa v27, v27, v29 dst_sel:DWORD dst_unused:UNUSED_PAD src0_sel:DWORD src1_sel:WORD_1
	v_or_b32_sdwa v26, v26, v28 dst_sel:DWORD dst_unused:UNUSED_PAD src0_sel:DWORD src1_sel:WORD_1
	v_mov_b32_e32 v250, v24
	v_mov_b32_e32 v251, v25
	v_mov_b32_e32 v252, v26
	v_mov_b32_e32 v253, v27
	v_lshl_add_u64 v[28:29], v[60:61], 0, v[52:53]
	global_load_dwordx4 v[24:27], v[38:39], off offset:2048
	v_lshl_add_u64 v[82:83], v[62:63], 0, v[52:53]
	global_load_dwordx4 v[28:31], v[28:29], off
	v_mov_b32_e32 v87, v22
	global_load_dwordx4 v[82:85], v[82:83], off
	global_store_dwordx2 v[250:251], v[252:253], off
	v_mov_b32_e32 v22, v21
	v_mov_b32_e32 v86, v20
	v_pk_mul_f32 v[22:23], v[22:23], v[96:97] op_sel_hi:[1,0]
	v_or_b32_e32 v20, v47, v75
	v_pk_mul_f32 v[86:87], v[86:87], v[96:97] op_sel_hi:[1,0]
	v_ashrrev_i32_e32 v21, 31, v20
	v_lshlrev_b64 v[20:21], 14, v[20:21]
	v_lshl_add_u64 v[20:21], s[62:63], 0, v[20:21]
	v_lshl_add_u64 v[20:21], v[20:21], 0, v[34:35]
	v_lshl_add_u64 v[20:21], v[20:21], 0, v[64:65]
	s_waitcnt vmcnt(3)
	v_mov_b32_e32 v89, v26
	v_mov_b32_e32 v26, v25
	s_waitcnt vmcnt(2)
	v_mov_b32_e32 v91, v30
	v_mov_b32_e32 v30, v29
	v_mov_b32_e32 v88, v24
	v_mov_b32_e32 v90, v28
	s_waitcnt vmcnt(1)
	v_mov_b32_e32 v93, v84
	v_mov_b32_e32 v84, v83
	v_pk_mul_f32 v[22:23], v[22:23], v[26:27]
	v_pk_add_f32 v[26:27], v[30:31], 1.0 op_sel_hi:[1,0]
	v_mov_b32_e32 v92, v82
	v_pk_mul_f32 v[24:25], v[86:87], v[88:89]
	v_pk_add_f32 v[28:29], v[90:91], 1.0 op_sel_hi:[1,0]
	v_pk_fma_f32 v[22:23], v[22:23], v[26:27], v[84:85]
	v_pk_fma_f32 v[24:25], v[24:25], v[28:29], v[92:93]
	v_and_b32_sdwa v28, v23, v80 dst_sel:DWORD dst_unused:UNUSED_PAD src0_sel:WORD_1 src1_sel:DWORD
	v_and_b32_sdwa v29, v22, v80 dst_sel:DWORD dst_unused:UNUSED_PAD src0_sel:WORD_1 src1_sel:DWORD
	v_and_b32_sdwa v26, v25, v80 dst_sel:DWORD dst_unused:UNUSED_PAD src0_sel:WORD_1 src1_sel:DWORD
	v_and_b32_sdwa v27, v24, v80 dst_sel:DWORD dst_unused:UNUSED_PAD src0_sel:WORD_1 src1_sel:DWORD
	v_add3_u32 v23, v23, v28, s19
	v_add3_u32 v22, v22, v29, s19
	v_add3_u32 v24, v24, v27, s19
	v_add3_u32 v25, v25, v26, s19
	v_and_b32_e32 v23, 0xffff0000, v23
	v_and_b32_e32 v22, 0xffff0000, v22
	v_or_b32_sdwa v23, v23, v25 dst_sel:DWORD dst_unused:UNUSED_PAD src0_sel:DWORD src1_sel:WORD_1
	v_or_b32_sdwa v22, v22, v24 dst_sel:DWORD dst_unused:UNUSED_PAD src0_sel:DWORD src1_sel:WORD_1
	v_mov_b32_e32 v250, v20
	v_mov_b32_e32 v251, v21
	v_mov_b32_e32 v252, v22
	v_mov_b32_e32 v253, v23
	v_lshl_add_u64 v[24:25], v[60:61], 0, v[56:57]
	global_load_dwordx4 v[20:23], v[38:39], off offset:3072
	v_lshl_add_u64 v[28:29], v[62:63], 0, v[56:57]
	global_load_dwordx4 v[24:27], v[24:25], off
	v_mov_b32_e32 v60, v16
	global_load_dwordx4 v[28:31], v[28:29], off
	global_store_dwordx2 v[250:251], v[252:253], off
	v_or_b32_e32 v16, v47, v76
	v_mov_b32_e32 v61, v18
	v_mov_b32_e32 v18, v17
	v_ashrrev_i32_e32 v17, 31, v16
	v_lshlrev_b64 v[16:17], 14, v[16:17]
	v_lshl_add_u64 v[16:17], s[62:63], 0, v[16:17]
	v_lshl_add_u64 v[16:17], v[16:17], 0, v[34:35]
	v_lshl_add_u64 v[16:17], v[16:17], 0, v[64:65]
	v_pk_mul_f32 v[18:19], v[18:19], v[96:97] op_sel_hi:[1,0]
	v_pk_mul_f32 v[60:61], v[60:61], v[96:97] op_sel_hi:[1,0]
	s_waitcnt vmcnt(3)
	v_mov_b32_e32 v63, v22
	v_mov_b32_e32 v22, v21
	s_waitcnt vmcnt(2)
	v_mov_b32_e32 v65, v26
	v_mov_b32_e32 v26, v25
	v_mov_b32_e32 v62, v20
	v_mov_b32_e32 v64, v24
	s_waitcnt vmcnt(1)
	v_mov_b32_e32 v83, v30
	v_mov_b32_e32 v30, v29
	v_pk_mul_f32 v[18:19], v[18:19], v[22:23]
	v_pk_add_f32 v[22:23], v[26:27], 1.0 op_sel_hi:[1,0]
	v_mov_b32_e32 v82, v28
	v_pk_mul_f32 v[20:21], v[60:61], v[62:63]
	v_pk_add_f32 v[24:25], v[64:65], 1.0 op_sel_hi:[1,0]
	v_pk_fma_f32 v[18:19], v[18:19], v[22:23], v[30:31]
	v_pk_fma_f32 v[20:21], v[20:21], v[24:25], v[82:83]
	v_and_b32_sdwa v24, v19, v80 dst_sel:DWORD dst_unused:UNUSED_PAD src0_sel:WORD_1 src1_sel:DWORD
	v_and_b32_sdwa v25, v18, v80 dst_sel:DWORD dst_unused:UNUSED_PAD src0_sel:WORD_1 src1_sel:DWORD
	v_and_b32_sdwa v22, v21, v80 dst_sel:DWORD dst_unused:UNUSED_PAD src0_sel:WORD_1 src1_sel:DWORD
	v_and_b32_sdwa v23, v20, v80 dst_sel:DWORD dst_unused:UNUSED_PAD src0_sel:WORD_1 src1_sel:DWORD
	v_add3_u32 v19, v19, v24, s19
	v_add3_u32 v18, v18, v25, s19
	v_add3_u32 v20, v20, v23, s19
	v_add3_u32 v21, v21, v22, s19
	v_and_b32_e32 v19, 0xffff0000, v19
	v_and_b32_e32 v18, 0xffff0000, v18
	v_or_b32_sdwa v19, v19, v21 dst_sel:DWORD dst_unused:UNUSED_PAD src0_sel:DWORD src1_sel:WORD_1
	v_or_b32_sdwa v18, v18, v20 dst_sel:DWORD dst_unused:UNUSED_PAD src0_sel:DWORD src1_sel:WORD_1
	global_store_dwordx2 v[16:17], v[18:19], off
	s_and_saveexec_b64 s[0:1], vcc
	s_cbranch_execz .LBB0_1419
; __device__ __forceinline__ u16 f2bf(float x) { unsigned u = __float_as_uint(x); u += 0x7fffu + ((u >> 16) & 1u); return (u16)(u >> 16); }
; __device__ __forceinline__ size_t a_off(int row, int col, int nks) { return ((size_t)((row >> 8) * nks + (col >> 5)) << 13) + ((row & 255) << 5) + swzc(row, col & 31); }
; template <int MODE>
; __device__ __forceinline__ void norm_phase(const Params& p, const float* src, const float* w, const float* modl, int sh_off, int sc_off,
;                            char* smem, int bid, int nblk) {
;     ...
;     for (int i = 0; i < 4; ++i) ss += v[i][0] * v[i][0] + v[i][1] * v[i][1] + v[i][2] * v[i][2] + v[i][3] * v[i][3];
; #pragma unroll
;     for (int o = 32; o >= 1; o >>= 1) ss += __shfl_xor(ss, o);
;     const float rstd = rsqrtf(ss * (1.f / 1024.f) + 1e-6f);
;     const int b = row >> 13;
;     float dots[8];
;     if (MODE == 1) { for (int j = 0; j < 8; ++j) dots[j] = 0.f; }
; #pragma unroll
;     for (int i = 0; i < 4; ++i) {
;       const int c0 = i * 256 + lane * 4;
;       f32x4 ww = *(const f32x4*)(w + c0);
;       f32x4 y;
;       if (MODE == 2) {
; #pragma unroll
;         for (int e = 0; e < 4; ++e) y[e] = v[i][e] * rstd * ww[e];
;         *(f32x4*)(p.out + (size_t)row * 1024 + c0) = y;
;       } else {
;         f32x4 sc = *(const f32x4*)(modl + (size_t)b * 6144 + sc_off + c0);
;         f32x4 sh = *(const f32x4*)(modl + (size_t)b * 6144 + sh_off + c0);
; #pragma unroll
;         for (int e = 0; e < 4; ++e) y[e] = v[i][e] * rstd * ww[e] * (1.f + sc[e]) + sh[e];
;         uint2 pk; pk.x = (unsigned)f2bf(y[0]) | ((unsigned)f2bf(y[1]) << 16); pk.y = (unsigned)f2bf(y[2]) | ((unsigned)f2bf(y[3]) << 16);
;         *(uint2*)(hn + a_off(row, c0, 32)) = pk;
;     ...
;   for (int row = bid * 4 + wid; row < M; row += nblk * 8) {
;     const int row1 = row + nblk * 4;
;     const bool has1 = row1 < M;
;     f32x4 v0[4], v1[4];
; #pragma unroll
;     for (int i = 0; i < 4; ++i) v0[i] = *(const f32x4*)(src + (size_t)row * 1024 + i * 256 + lane * 4);
; #pragma unroll
;     for (int i = 0; i < 4; ++i) v1[i] = has1 ? *(const f32x4*)(src + (size_t)row1 * 1024 + i * 256 + lane * 4) : f32x4{0.f, 0.f, 0.f, 0.f};
;     process(row, v0);
;     if (has1) process(row1, v1);
	v_ashrrev_i32_e32 v16, 13, v58
	v_mul_i32_i24_e32 v16, 0x1800, v16
	v_readlane_b32 s20, v244, 23
	v_ashrrev_i32_e32 v17, 31, v16
	v_readlane_b32 s21, v244, 24
	v_mov_b32_e32 v43, v35
	global_load_dwordx4 v[22:25], v[38:39], off
	v_lshl_add_u64 v[18:19], v[16:17], 2, s[20:21]
	v_lshl_add_u64 v[16:17], v[18:19], 0, s[12:13]
	v_lshl_add_u64 v[26:27], v[16:17], 0, v[42:43]
	v_lshl_add_u64 v[18:19], v[18:19], 0, s[14:15]
	global_load_dwordx4 v[26:29], v[26:27], off
	v_lshl_add_u64 v[30:31], v[18:19], 0, v[42:43]
	global_load_dwordx4 v[60:63], v[30:31], off
	v_pk_mul_f32 v[64:65], v[8:9], v[8:9]
	v_pk_mul_f32 v[82:83], v[12:13], v[12:13]
	v_pk_mul_f32 v[20:21], v[14:15], v[14:15]
	v_pk_mul_f32 v[30:31], v[10:11], v[10:11]
	v_mov_b32_e32 v84, v82
	v_mov_b32_e32 v85, v64
	v_mov_b32_e32 v64, v83
	v_pk_add_f32 v[64:65], v[84:85], v[64:65]
	v_mov_b32_e32 v82, v20
	v_mov_b32_e32 v83, v30
	v_pk_add_f32 v[64:65], v[82:83], v[64:65]
	v_mov_b32_e32 v30, v21
	v_pk_add_f32 v[20:21], v[30:31], v[64:65]
	v_mov_b32_e32 v64, v5
	v_mov_b32_e32 v65, v1
	v_mov_b32_e32 v30, v4
	v_mov_b32_e32 v31, v0
	v_pk_mul_f32 v[64:65], v[64:65], v[64:65]
	v_add_f32_e32 v20, v20, v21
	v_pk_fma_f32 v[30:31], v[30:31], v[30:31], v[64:65]
	v_mov_b32_e32 v64, v6
	v_mov_b32_e32 v65, v2
	v_pk_fma_f32 v[30:31], v[64:65], v[64:65], v[30:31]
	v_mov_b32_e32 v64, v7
	v_mov_b32_e32 v65, v3
	v_pk_fma_f32 v[30:31], v[64:65], v[64:65], v[30:31]
	v_ashrrev_i32_e32 v34, 3, v58
	v_add_f32_e32 v20, v30, v20
	v_add_f32_e32 v20, v20, v31
	s_nop 1
	v_mov_b32_e32 v21, v20
	s_nop 1
	v_permlane32_swap_b32_e32 v20, v21
	v_mov_b32_e32 v30, v12
	v_add_u32_e32 v43, s7, v78
	v_add_u32_e32 v47, s6, v77
	v_and_b32_e32 v81, 0xffffffe0, v34
	s_waitcnt lgkmcnt(0)
	v_add_f32_e32 v20, v20, v21
	s_nop 1
	v_mov_b32_e32 v21, v20
	s_nop 1
	v_permlane16_swap_b32_e32 v20, v21
	v_and_b32_e32 v34, 24, v47
	v_or_b32_e32 v58, v81, v72
	v_ashrrev_i32_e32 v59, 31, v58
	v_lshlrev_b64 v[58:59], 14, v[58:59]
	s_waitcnt lgkmcnt(0)
	v_add_f32_e32 v20, v20, v21
	s_nop 1
	v_mov_b32_dpp v31, v20 row_ror:8 row_mask:0xf bank_mask:0xf
	v_lshl_add_u64 v[58:59], s[62:63], 0, v[58:59]
	v_mov_b32_e32 v21, v35
	v_mov_b32_e32 v47, v35
	v_mov_b32_e32 v51, v35
	s_waitcnt lgkmcnt(0)
	v_add_f32_e32 v12, v20, v31
	s_nop 1
	v_mov_b32_dpp v20, v12 row_ror:4 row_mask:0xf bank_mask:0xf
	v_mov_b32_e32 v31, v14
	v_and_b32_e32 v14, 0x1fe0, v43
	v_sub_u32_e32 v43, 0, v34
	v_lshlrev_b32_e32 v34, 1, v14
	s_waitcnt lgkmcnt(0)
	v_add_f32_e32 v12, v12, v20
	s_nop 1
	v_mov_b32_dpp v20, v12 quad_perm:[2,3,0,1] row_mask:0xf bank_mask:0xf
	v_lshl_add_u64 v[58:59], v[58:59], 0, v[34:35]
	v_mov_b32_e32 v55, v35
	s_waitcnt lgkmcnt(0)
	v_add_f32_e32 v12, v12, v20
	s_nop 1
	v_mov_b32_dpp v14, v12 quad_perm:[1,0,3,2] row_mask:0xf bank_mask:0xf
	v_xor_b32_e32 v20, v32, v43
	v_and_or_b32 v20, v20, 24, v73
	v_lshlrev_b32_e32 v20, 1, v20
	v_lshl_add_u64 v[58:59], v[58:59], 0, v[20:21]
	s_waitcnt lgkmcnt(0)
	v_add_f32_e32 v12, v12, v14
	v_fmamk_f32 v12, v12, 0x3a800000, v79
	v_mul_f32_e32 v14, 0x4b800000, v12
	v_cmp_gt_f32_e32 vcc, s18, v12
	s_waitcnt vmcnt(2)
	v_mov_b32_e32 v64, v22
	v_cndmask_b32_e32 v12, v12, v14, vcc
	v_rsq_f32_e32 v12, v12
	v_mov_b32_e32 v65, v24
	v_mov_b32_e32 v24, v23
	v_mul_f32_e32 v14, 0x45800000, v12
	v_cndmask_b32_e32 v12, v12, v14, vcc
	v_pk_mul_f32 v[30:31], v[30:31], v[12:13] op_sel_hi:[1,0]
	v_mov_b32_e32 v14, v13
	v_pk_mul_f32 v[30:31], v[64:65], v[30:31]
	s_waitcnt vmcnt(1)
	v_mov_b32_e32 v65, v28
	v_pk_mul_f32 v[14:15], v[14:15], v[12:13] op_sel_hi:[1,0]
	v_mov_b32_e32 v28, v27
	v_mov_b32_e32 v64, v26
	s_waitcnt vmcnt(0)
	v_mov_b32_e32 v83, v62
	v_pk_mul_f32 v[14:15], v[24:25], v[14:15]
	v_pk_add_f32 v[22:23], v[28:29], 1.0 op_sel_hi:[1,0]
	v_mov_b32_e32 v62, v61
	v_mov_b32_e32 v82, v60
	v_pk_add_f32 v[64:65], v[64:65], 1.0 op_sel_hi:[1,0]
	v_pk_fma_f32 v[14:15], v[22:23], v[14:15], v[62:63]
	v_pk_fma_f32 v[30:31], v[64:65], v[30:31], v[82:83]
	v_and_b32_sdwa v23, v15, v80 dst_sel:DWORD dst_unused:UNUSED_PAD src0_sel:WORD_1 src1_sel:DWORD
	v_and_b32_sdwa v24, v14, v80 dst_sel:DWORD dst_unused:UNUSED_PAD src0_sel:WORD_1 src1_sel:DWORD
	v_and_b32_sdwa v13, v31, v80 dst_sel:DWORD dst_unused:UNUSED_PAD src0_sel:WORD_1 src1_sel:DWORD
	v_and_b32_sdwa v22, v30, v80 dst_sel:DWORD dst_unused:UNUSED_PAD src0_sel:WORD_1 src1_sel:DWORD
	v_add3_u32 v15, v15, v23, s19
	v_add3_u32 v14, v14, v24, s19
	v_add3_u32 v22, v30, v22, s19
	v_add3_u32 v13, v31, v13, s19
	v_and_b32_e32 v15, 0xffff0000, v15
	v_and_b32_e32 v14, 0xffff0000, v14
	v_or_b32_sdwa v15, v15, v13 dst_sel:DWORD dst_unused:UNUSED_PAD src0_sel:DWORD src1_sel:WORD_1
	v_or_b32_sdwa v14, v14, v22 dst_sel:DWORD dst_unused:UNUSED_PAD src0_sel:DWORD src1_sel:WORD_1
	v_mov_b32_e32 v250, v58
	v_mov_b32_e32 v251, v59
	v_mov_b32_e32 v252, v14
	v_mov_b32_e32 v253, v15
	v_lshl_add_u64 v[14:15], v[16:17], 0, v[46:47]
	global_load_dwordx4 v[22:25], v[38:39], off offset:1024
	global_load_dwordx4 v[26:29], v[14:15], off
	v_lshl_add_u64 v[14:15], v[18:19], 0, v[46:47]
	global_load_dwordx4 v[58:61], v[14:15], off
	global_store_dwordx2 v[250:251], v[252:253], off
	v_mov_b32_e32 v15, v10
	v_mov_b32_e32 v10, v9
	v_mov_b32_e32 v14, v8
	v_pk_mul_f32 v[10:11], v[10:11], v[12:13] op_sel_hi:[1,0]
	v_or_b32_e32 v8, v81, v74
	v_pk_mul_f32 v[14:15], v[14:15], v[12:13] op_sel_hi:[1,0]
	v_ashrrev_i32_e32 v9, 31, v8
	v_lshlrev_b64 v[8:9], 14, v[8:9]
	v_lshl_add_u64 v[8:9], s[62:63], 0, v[8:9]
	v_lshl_add_u64 v[8:9], v[8:9], 0, v[34:35]
	v_lshl_add_u64 v[8:9], v[8:9], 0, v[20:21]
	s_waitcnt vmcnt(3)
	v_mov_b32_e32 v31, v24
	s_waitcnt vmcnt(2)
; __device__ __forceinline__ u16 f2bf(float x) { unsigned u = __float_as_uint(x); u += 0x7fffu + ((u >> 16) & 1u); return (u16)(u >> 16); }
; __device__ __forceinline__ size_t a_off(int row, int col, int nks) { return ((size_t)((row >> 8) * nks + (col >> 5)) << 13) + ((row & 255) << 5) + swzc(row, col & 31); }
; template <int MODE>
; __device__ __forceinline__ void norm_phase(const Params& p, const float* src, const float* w, const float* modl, int sh_off, int sc_off,
;                            char* smem, int bid, int nblk) {
;     ...
;     for (int i = 0; i < 4; ++i) {
;       const int c0 = i * 256 + lane * 4;
;       f32x4 ww = *(const f32x4*)(w + c0);
;       f32x4 y;
;       if (MODE == 2) {
; #pragma unroll
;         for (int e = 0; e < 4; ++e) y[e] = v[i][e] * rstd * ww[e];
;         *(f32x4*)(p.out + (size_t)row * 1024 + c0) = y;
;       } else {
;         f32x4 sc = *(const f32x4*)(modl + (size_t)b * 6144 + sc_off + c0);
;         f32x4 sh = *(const f32x4*)(modl + (size_t)b * 6144 + sh_off + c0);
; #pragma unroll
;         for (int e = 0; e < 4; ++e) y[e] = v[i][e] * rstd * ww[e] * (1.f + sc[e]) + sh[e];
;         uint2 pk; pk.x = (unsigned)f2bf(y[0]) | ((unsigned)f2bf(y[1]) << 16); pk.y = (unsigned)f2bf(y[2]) | ((unsigned)f2bf(y[3]) << 16);
;         *(uint2*)(hn + a_off(row, c0, 32)) = pk;
	v_mov_b32_e32 v63, v28
	v_mov_b32_e32 v24, v23
	v_mov_b32_e32 v28, v27
	v_mov_b32_e32 v30, v22
	v_mov_b32_e32 v62, v26
	s_waitcnt vmcnt(1)
	v_mov_b32_e32 v65, v60
	v_mov_b32_e32 v60, v59
	v_pk_mul_f32 v[10:11], v[24:25], v[10:11]
	v_pk_add_f32 v[24:25], v[28:29], 1.0 op_sel_hi:[1,0]
	v_mov_b32_e32 v64, v58
	v_pk_mul_f32 v[14:15], v[30:31], v[14:15]
	v_pk_add_f32 v[22:23], v[62:63], 1.0 op_sel_hi:[1,0]
	v_pk_fma_f32 v[10:11], v[24:25], v[10:11], v[60:61]
	v_pk_fma_f32 v[14:15], v[22:23], v[14:15], v[64:65]
	v_and_b32_sdwa v23, v11, v80 dst_sel:DWORD dst_unused:UNUSED_PAD src0_sel:WORD_1 src1_sel:DWORD
	v_and_b32_sdwa v24, v10, v80 dst_sel:DWORD dst_unused:UNUSED_PAD src0_sel:WORD_1 src1_sel:DWORD
	v_and_b32_sdwa v13, v15, v80 dst_sel:DWORD dst_unused:UNUSED_PAD src0_sel:WORD_1 src1_sel:DWORD
	v_and_b32_sdwa v22, v14, v80 dst_sel:DWORD dst_unused:UNUSED_PAD src0_sel:WORD_1 src1_sel:DWORD
	v_add3_u32 v11, v11, v23, s19
	v_add3_u32 v10, v10, v24, s19
	v_add3_u32 v14, v14, v22, s19
	v_add3_u32 v13, v15, v13, s19
	v_and_b32_e32 v11, 0xffff0000, v11
	v_and_b32_e32 v10, 0xffff0000, v10
	v_or_b32_sdwa v11, v11, v13 dst_sel:DWORD dst_unused:UNUSED_PAD src0_sel:DWORD src1_sel:WORD_1
	v_or_b32_sdwa v10, v10, v14 dst_sel:DWORD dst_unused:UNUSED_PAD src0_sel:DWORD src1_sel:WORD_1
	v_mov_b32_e32 v250, v8
	v_mov_b32_e32 v251, v9
	v_mov_b32_e32 v252, v10
	v_mov_b32_e32 v253, v11
	v_lshl_add_u64 v[14:15], v[16:17], 0, v[50:51]
	global_load_dwordx4 v[8:11], v[38:39], off offset:2048
	global_load_dwordx4 v[22:25], v[14:15], off
	v_lshl_add_u64 v[14:15], v[18:19], 0, v[50:51]
	global_load_dwordx4 v[26:29], v[14:15], off
	global_store_dwordx2 v[250:251], v[252:253], off
	v_mov_b32_e32 v15, v6
	v_mov_b32_e32 v6, v5
	v_mov_b32_e32 v14, v4
	v_pk_mul_f32 v[6:7], v[6:7], v[12:13] op_sel_hi:[1,0]
	v_or_b32_e32 v4, v81, v75
	v_pk_mul_f32 v[14:15], v[14:15], v[12:13] op_sel_hi:[1,0]
	v_ashrrev_i32_e32 v5, 31, v4
	v_lshlrev_b64 v[4:5], 14, v[4:5]
	v_lshl_add_u64 v[4:5], s[62:63], 0, v[4:5]
	v_lshl_add_u64 v[4:5], v[4:5], 0, v[34:35]
	v_lshl_add_u64 v[4:5], v[4:5], 0, v[20:21]
	s_waitcnt vmcnt(3)
	v_mov_b32_e32 v31, v10
	s_waitcnt vmcnt(2)
	v_mov_b32_e32 v59, v24
	v_mov_b32_e32 v10, v9
	v_mov_b32_e32 v24, v23
	v_mov_b32_e32 v30, v8
	v_mov_b32_e32 v58, v22
	s_waitcnt vmcnt(1)
	v_mov_b32_e32 v61, v28
	v_mov_b32_e32 v28, v27
	v_pk_mul_f32 v[6:7], v[6:7], v[10:11]
	v_pk_add_f32 v[10:11], v[24:25], 1.0 op_sel_hi:[1,0]
	v_mov_b32_e32 v60, v26
	v_pk_mul_f32 v[8:9], v[14:15], v[30:31]
	v_pk_add_f32 v[14:15], v[58:59], 1.0 op_sel_hi:[1,0]
	v_pk_fma_f32 v[6:7], v[6:7], v[10:11], v[28:29]
	v_pk_fma_f32 v[8:9], v[8:9], v[14:15], v[60:61]
	v_and_b32_sdwa v13, v7, v80 dst_sel:DWORD dst_unused:UNUSED_PAD src0_sel:WORD_1 src1_sel:DWORD
	v_and_b32_sdwa v14, v6, v80 dst_sel:DWORD dst_unused:UNUSED_PAD src0_sel:WORD_1 src1_sel:DWORD
	v_and_b32_sdwa v10, v9, v80 dst_sel:DWORD dst_unused:UNUSED_PAD src0_sel:WORD_1 src1_sel:DWORD
	v_and_b32_sdwa v11, v8, v80 dst_sel:DWORD dst_unused:UNUSED_PAD src0_sel:WORD_1 src1_sel:DWORD
	v_add3_u32 v7, v7, v13, s19
	v_add3_u32 v6, v6, v14, s19
	v_add3_u32 v8, v8, v11, s19
	v_add3_u32 v9, v9, v10, s19
	v_and_b32_e32 v7, 0xffff0000, v7
	v_and_b32_e32 v6, 0xffff0000, v6
	v_or_b32_sdwa v7, v7, v9 dst_sel:DWORD dst_unused:UNUSED_PAD src0_sel:DWORD src1_sel:WORD_1
	v_or_b32_sdwa v6, v6, v8 dst_sel:DWORD dst_unused:UNUSED_PAD src0_sel:DWORD src1_sel:WORD_1
	v_mov_b32_e32 v250, v4
	v_mov_b32_e32 v251, v5
	v_mov_b32_e32 v252, v6
	v_mov_b32_e32 v253, v7
	v_lshl_add_u64 v[8:9], v[16:17], 0, v[54:55]
	global_load_dwordx4 v[4:7], v[38:39], off offset:3072
	v_lshl_add_u64 v[14:15], v[18:19], 0, v[54:55]
	global_load_dwordx4 v[8:11], v[8:9], off
	v_mov_b32_e32 v18, v0
	global_load_dwordx4 v[14:17], v[14:15], off
	global_store_dwordx2 v[250:251], v[252:253], off
	v_or_b32_e32 v0, v81, v76
	v_mov_b32_e32 v19, v2
	v_mov_b32_e32 v2, v1
	v_ashrrev_i32_e32 v1, 31, v0
	v_lshlrev_b64 v[0:1], 14, v[0:1]
	v_lshl_add_u64 v[0:1], s[62:63], 0, v[0:1]
	v_lshl_add_u64 v[0:1], v[0:1], 0, v[34:35]
	v_lshl_add_u64 v[0:1], v[0:1], 0, v[20:21]
	v_pk_mul_f32 v[18:19], v[18:19], v[12:13] op_sel_hi:[1,0]
	v_pk_mul_f32 v[2:3], v[2:3], v[12:13] op_sel_hi:[1,0]
	s_waitcnt vmcnt(3)
	v_mov_b32_e32 v13, v6
	v_mov_b32_e32 v6, v5
	s_waitcnt vmcnt(2)
	v_mov_b32_e32 v21, v10
	v_mov_b32_e32 v10, v9
	v_mov_b32_e32 v12, v4
	v_mov_b32_e32 v20, v8
	s_waitcnt vmcnt(1)
	v_mov_b32_e32 v23, v16
	v_mov_b32_e32 v16, v15
	v_pk_mul_f32 v[2:3], v[2:3], v[6:7]
	v_pk_add_f32 v[6:7], v[10:11], 1.0 op_sel_hi:[1,0]
	v_mov_b32_e32 v22, v14
	v_pk_mul_f32 v[4:5], v[18:19], v[12:13]
	v_pk_add_f32 v[8:9], v[20:21], 1.0 op_sel_hi:[1,0]
	v_pk_fma_f32 v[2:3], v[2:3], v[6:7], v[16:17]
	v_pk_fma_f32 v[4:5], v[4:5], v[8:9], v[22:23]
	v_and_b32_sdwa v8, v3, v80 dst_sel:DWORD dst_unused:UNUSED_PAD src0_sel:WORD_1 src1_sel:DWORD
	v_and_b32_sdwa v9, v2, v80 dst_sel:DWORD dst_unused:UNUSED_PAD src0_sel:WORD_1 src1_sel:DWORD
	v_and_b32_sdwa v6, v5, v80 dst_sel:DWORD dst_unused:UNUSED_PAD src0_sel:WORD_1 src1_sel:DWORD
	v_and_b32_sdwa v7, v4, v80 dst_sel:DWORD dst_unused:UNUSED_PAD src0_sel:WORD_1 src1_sel:DWORD
	v_add3_u32 v3, v3, v8, s19
	v_add3_u32 v2, v2, v9, s19
	v_add3_u32 v4, v4, v7, s19
	v_add3_u32 v5, v5, v6, s19
	v_and_b32_e32 v3, 0xffff0000, v3
	v_and_b32_e32 v2, 0xffff0000, v2
	v_or_b32_sdwa v3, v3, v5 dst_sel:DWORD dst_unused:UNUSED_PAD src0_sel:DWORD src1_sel:WORD_1
	v_or_b32_sdwa v2, v2, v4 dst_sel:DWORD dst_unused:UNUSED_PAD src0_sel:DWORD src1_sel:WORD_1
	global_store_dwordx2 v[0:1], v[2:3], off
	s_branch .LBB0_1419
